# phase_norm loops: all gain/scale/shift loads issued with the row's x loads (one wait per row instead of four)
# speedup vs baseline: 1.0126x; 1.0025x over previous
; __device__ __forceinline__ void phase_norm(const Frame& F, const Params& P, int l, int which, int nrows, bf16_t* HB) {
;     ...
;         const float* xr = (row < NLAT) ? xl + (size_t)row * 1024 : xc + (size_t)(row - NLAT) * 1024;
;         const int mb = (row < NLAT) ? (row >> 13) : 4;
;         const float* sh = MOD + mb * 6144 + (which ? 3072 : 0); const float* sc = sh + 1024;
;         f32x4 v[4]; float ss = 0.f;
; #pragma unroll
;         for (int j = 0; j < 4; ++j) v[j] = *(const f32x4*)(xr + 4 * F.lane + 256 * j);
;         if (l == 0 && which == 1 && row >= NLAT) {
;             const float* cin = P.in[2] + (size_t)(row - NLAT) * 1024 + 4 * F.lane;
;             const float* pp = (const float*)(P.ws + WS_AR + AR_PG4) + (size_t)(row - NLAT) * 1024 + 4 * F.lane;
;             float* xo = (float*)(P.ws + WS_XC) + (size_t)(row - NLAT) * 1024 + 4 * F.lane;
; #pragma unroll
;             for (int j = 0; j < 4; ++j) {
;                 v[j] = *(const f32x4*)(cin + 256 * j);
; #pragma unroll
;                 for (int kp = 0; kp < 3; ++kp) v[j] += *(const f32x4*)(pp + (size_t)kp * NCTX * 1024 + 256 * j);
;                 *(f32x4*)(xo + 256 * j) = v[j];
;             }
;         }
;         if (l == 1 && which == 0 && row >= NLAT) {
;             const float* pp = (const float*)(P.ws + WS_AR + AR_PART) + (size_t)(row - NLAT) * 1024 + 4 * F.lane;
; #pragma unroll
;             for (int kp = 0; kp < 4; ++kp)
; #pragma unroll
;                 for (int j = 0; j < 4; ++j) v[j] += *(const f32x4*)(pp + (size_t)kp * NCTX * 1024 + 256 * j);
;         }
; #pragma unroll
;         for (int j = 0; j < 4; ++j) ss += (v[j][0] * v[j][0] + v[j][1] * v[j][1]) + (v[j][2] * v[j][2] + v[j][3] * v[j][3]);
;         ss = wave_sum(ss); const float rinv = rsqrtf(ss * (1.0f / 1024.0f) + EPS);
; #pragma unroll
;         for (int j = 0; j < 4; ++j) {
;             const int col = 4 * F.lane + 256 * j;
;             const f32x4 g = *(const f32x4*)(gn + col), s1 = *(const f32x4*)(sc + col), s0 = *(const f32x4*)(sh + col);
;             const f32x4 y = v[j] * rinv * g * (s1 + 1.0f) + s0;
;             u32x2 w; w.x = cvt_pk_bf16(y[0], y[1]); w.y = cvt_pk_bf16(y[2], y[3]);
;             *(u32x2*)(H + (size_t)row * 1024 + col) = w;
;             if (HB && (((row + 2) & 127) < 4)) *(u32x2*)(HB + (size_t)(4 * ((row + 2) >> 7) + ((row + 2) & 127)) * 1024 + col) = w;
;         }
.LBB0_162:
	s_min_i32 s0, s6, 0x8000
	s_ashr_i32 s0, s0, 13
	s_mulk_i32 s0, 0x1800
	s_ashr_i32 s1, s0, 31
	s_lshl_b64 s[0:1], s[0:1], 2
	v_readlane_b32 s12, v253, 63
	s_add_u32 s0, s12, s0
	v_readlane_b32 s12, v254, 1
	s_addc_u32 s1, s12, s1
	s_add_u32 s12, s0, 0x1000
	s_addc_u32 s13, s1, 0
	global_load_dwordx4 v[40:43], v[22:23], off
	s_nop 0
	global_load_dwordx4 v[44:47], v192, s[12:13]
	global_load_dwordx4 v[48:51], v192, s[0:1]
	global_load_dwordx4 v[100:103], v[24:25], off
	global_load_dwordx4 v[104:107], v17, s[12:13]
	global_load_dwordx4 v[108:111], v192, s[0:1] offset:1024
	global_load_dwordx4 v[112:115], v[26:27], off
	global_load_dwordx4 v[116:119], v38, s[12:13]
	global_load_dwordx4 v[120:123], v192, s[0:1] offset:2048
	global_load_dwordx4 v[124:127], v[28:29], off
	global_load_dwordx4 v[128:131], v39, s[12:13]
	global_load_dwordx4 v[132:135], v192, s[0:1] offset:3072
	s_waitcnt vmcnt(0)
	v_mul_f32_e32 v34, v1, v1
	v_mul_f32_e32 v35, v3, v3
	v_fmac_f32_e32 v34, v0, v0
	v_fmac_f32_e32 v35, v2, v2
	v_add_f32_e32 v34, v34, v35
	v_mul_f32_e32 v35, v9, v9
	v_mul_f32_e32 v36, v11, v11
	v_fmac_f32_e32 v35, v8, v8
	v_fmac_f32_e32 v36, v10, v10
	v_add_f32_e32 v35, v35, v36
	v_add_f32_e32 v34, v34, v35
	v_mul_f32_e32 v35, v5, v5
	v_mul_f32_e32 v36, v7, v7
	v_fmac_f32_e32 v35, v4, v4
	v_fmac_f32_e32 v36, v6, v6
	v_add_f32_e32 v35, v35, v36
	v_add_f32_e32 v34, v35, v34
	v_mul_f32_e32 v35, v13, v13
	v_mul_f32_e32 v36, v15, v15
	v_fmac_f32_e32 v35, v12, v12
	v_fmac_f32_e32 v36, v14, v14
	v_add_f32_e32 v35, v35, v36
	v_add_f32_e32 v34, v35, v34
	ds_swizzle_b32 v35, v34 offset:swizzle(SWAP,1)
	s_mov_b32 s14, 0x800000
	s_waitcnt lgkmcnt(0)
	v_add_f32_e32 v34, v34, v35
	ds_swizzle_b32 v35, v34 offset:swizzle(SWAP,2)
	s_waitcnt lgkmcnt(0)
	v_add_f32_e32 v34, v34, v35
	ds_swizzle_b32 v35, v34 offset:swizzle(SWAP,4)
	s_waitcnt lgkmcnt(0)
	v_add_f32_e32 v34, v34, v35
	ds_swizzle_b32 v35, v34 offset:swizzle(SWAP,8)
	s_waitcnt lgkmcnt(0)
	v_add_f32_e32 v34, v34, v35
	ds_swizzle_b32 v35, v34 offset:swizzle(SWAP,16)
	s_waitcnt lgkmcnt(0)
	v_add_f32_e32 v34, v34, v35
	v_mov_b32_e32 v35, v34
	s_nop 1
	v_permlane32_swap_b32_e32 v34, v35
	v_add_f32_e32 v34, v34, v35
	v_fmamk_f32 v34, v34, 0x3a800000, v226
	v_cmp_gt_f32_e32 vcc, s14, v34
	v_mul_f32_e32 v35, 0x4b800000, v34
	s_add_i32 s14, s6, 2
	v_cndmask_b32_e32 v34, v34, v35, vcc
	v_rsq_f32_e32 v34, v34
	s_and_b32 s18, s14, 0x7f
	s_cmp_lt_u32 s18, 4
	s_cselect_b64 s[16:17], -1, 0
	s_ashr_i32 s14, s14, 5
	s_and_b32 s14, s14, -4
	v_mul_f32_e32 v35, 0x45800000, v34
	s_or_b32 s14, s14, s18
	v_cndmask_b32_e32 v34, v34, v35, vcc
	s_ashr_i32 s15, s14, 31
	s_lshl_b64 s[14:15], s[14:15], 11
	v_pk_mul_f32 v[2:3], v[2:3], v[34:35] op_sel_hi:[1,0]
	v_pk_mul_f32 v[0:1], v[0:1], v[34:35] op_sel_hi:[1,0]
	s_add_u32 s14, s2, s14
	s_addc_u32 s15, s3, s15
	v_pk_mul_f32 v[0:1], v[40:41], v[0:1]
	v_pk_mul_f32 v[2:3], v[42:43], v[2:3]
	v_pk_add_f32 v[36:37], v[46:47], 1.0 op_sel_hi:[1,0]
	v_pk_add_f32 v[40:41], v[44:45], 1.0 op_sel_hi:[1,0]
	v_pk_fma_f32 v[36:37], v[36:37], v[2:3], v[50:51]
	v_pk_fma_f32 v[0:1], v[40:41], v[0:1], v[48:49]
	s_cmp_gt_u32 s18, 3
	v_cvt_pk_bf16_f32 v2, v0, v1
	v_cvt_pk_bf16_f32 v3, v36, v37
	v_lshlrev_b32_e32 v0, 1, v16
	global_store_dwordx2 v[32:33], v[2:3], off
	s_cbranch_scc1 .LBB0_164
	v_mov_b32_e32 v1, v193
	v_lshl_add_u64 v[36:37], s[14:15], 0, v[0:1]
	flat_store_dwordx2 v[36:37], v[2:3]
.LBB0_164:
	v_lshl_add_u64 v[2:3], s[0:1], 0, v[192:193]
	v_mov_b32_e32 v35, v34
	v_mov_b32_e32 v36, v34
	v_mov_b32_e32 v37, v34
	v_pk_mul_f32 v[10:11], v[10:11], v[36:37]
	v_pk_mul_f32 v[8:9], v[8:9], v[34:35]
	v_cndmask_b32_e64 v1, 0, 1, s[16:17]
	v_cmp_ne_u32_e64 s[0:1], 1, v1
	s_andn2_b64 vcc, exec, s[16:17]
	v_mov_b32_e32 v40, v100
	v_mov_b32_e32 v41, v101
	v_mov_b32_e32 v42, v102
	v_mov_b32_e32 v43, v103
	v_mov_b32_e32 v44, v104
	v_mov_b32_e32 v45, v105
	v_mov_b32_e32 v46, v106
	v_mov_b32_e32 v47, v107
	v_mov_b32_e32 v48, v108
	v_mov_b32_e32 v49, v109
	v_mov_b32_e32 v50, v110
	v_mov_b32_e32 v51, v111
	v_pk_mul_f32 v[10:11], v[10:11], v[42:43]
	v_pk_mul_f32 v[8:9], v[8:9], v[40:41]
	v_pk_add_f32 v[40:41], v[46:47], 1.0 op_sel_hi:[1,0]
	v_pk_add_f32 v[42:43], v[44:45], 1.0 op_sel_hi:[1,0]
	v_pk_fma_f32 v[10:11], v[10:11], v[40:41], v[50:51]
	v_pk_fma_f32 v[8:9], v[8:9], v[42:43], v[48:49]
	s_nop 0
	v_cvt_pk_bf16_f32 v8, v8, v9
	v_cvt_pk_bf16_f32 v9, v10, v11
	global_store_dwordx2 v[32:33], v[8:9], off offset:512
	s_cbranch_vccnz .LBB0_166
	v_mov_b32_e32 v1, v193
	v_lshl_add_u64 v[10:11], s[14:15], 0, v[0:1]
	flat_store_dwordx2 v[10:11], v[8:9] offset:512
.LBB0_166:
	s_nop 0
	v_pk_mul_f32 v[6:7], v[6:7], v[36:37]
	v_pk_mul_f32 v[4:5], v[4:5], v[34:35]
	s_and_b64 vcc, exec, s[0:1]
	v_mov_b32_e32 v8, v112
	v_mov_b32_e32 v9, v113
	v_mov_b32_e32 v10, v114
	v_mov_b32_e32 v11, v115
	v_mov_b32_e32 v40, v116
	v_mov_b32_e32 v41, v117
	v_mov_b32_e32 v42, v118
	v_mov_b32_e32 v43, v119
	v_mov_b32_e32 v44, v120
	v_mov_b32_e32 v45, v121
	v_mov_b32_e32 v46, v122
	v_mov_b32_e32 v47, v123
	v_pk_mul_f32 v[6:7], v[6:7], v[10:11]
	v_pk_mul_f32 v[4:5], v[4:5], v[8:9]
	v_pk_add_f32 v[8:9], v[42:43], 1.0 op_sel_hi:[1,0]
	v_pk_add_f32 v[10:11], v[40:41], 1.0 op_sel_hi:[1,0]
	v_pk_fma_f32 v[6:7], v[6:7], v[8:9], v[46:47]
	v_pk_fma_f32 v[4:5], v[4:5], v[10:11], v[44:45]
	s_nop 0
	v_cvt_pk_bf16_f32 v4, v4, v5
	v_cvt_pk_bf16_f32 v5, v6, v7
	global_store_dwordx2 v[32:33], v[4:5], off offset:1024
	s_cbranch_vccnz .LBB0_168
	v_mov_b32_e32 v1, v193
	v_lshl_add_u64 v[6:7], s[14:15], 0, v[0:1]
	flat_store_dwordx2 v[6:7], v[4:5] offset:1024
.LBB0_168:
	s_nop 0
	v_mov_b32_e32 v2, v34
	v_mov_b32_e32 v3, v34
	v_pk_mul_f32 v[12:13], v[12:13], v[34:35]
	v_pk_mul_f32 v[2:3], v[14:15], v[2:3]
	s_and_b64 vcc, exec, s[0:1]
	v_mov_b32_e32 v4, v124
	v_mov_b32_e32 v5, v125
	v_mov_b32_e32 v6, v126
	v_mov_b32_e32 v7, v127
	v_mov_b32_e32 v8, v128
	v_mov_b32_e32 v9, v129
	v_mov_b32_e32 v10, v130
	v_mov_b32_e32 v11, v131
	v_mov_b32_e32 v40, v132
	v_mov_b32_e32 v41, v133
	v_mov_b32_e32 v42, v134
	v_mov_b32_e32 v43, v135
	v_pk_mul_f32 v[2:3], v[2:3], v[6:7]
	v_pk_mul_f32 v[4:5], v[12:13], v[4:5]
	v_pk_add_f32 v[6:7], v[10:11], 1.0 op_sel_hi:[1,0]
	v_pk_add_f32 v[8:9], v[8:9], 1.0 op_sel_hi:[1,0]
	v_pk_fma_f32 v[6:7], v[2:3], v[6:7], v[42:43]
	v_pk_fma_f32 v[2:3], v[4:5], v[8:9], v[40:41]
	s_nop 0
	v_cvt_pk_bf16_f32 v2, v2, v3
	v_cvt_pk_bf16_f32 v3, v6, v7
	global_store_dwordx2 v[32:33], v[2:3], off offset:1536
	s_cbranch_vccnz .LBB0_159
	v_mov_b32_e32 v1, v193
	v_lshl_add_u64 v[0:1], s[14:15], 0, v[0:1]
	flat_store_dwordx2 v[0:1], v[2:3] offset:1536
	s_branch .LBB0_159

; __device__ __forceinline__ void phase_norm(const Frame& F, const Params& P, int l, int which, int nrows, bf16_t* HB) {
;     ...
;     for (int row = gw; row < nrows; row += NGW) {
;         const float* xr = (row < NLAT) ? xl + (size_t)row * 1024 : xc + (size_t)(row - NLAT) * 1024;
;         const int mb = (row < NLAT) ? (row >> 13) : 4;
;         const float* sh = MOD + mb * 6144 + (which ? 3072 : 0); const float* sc = sh + 1024;
;         f32x4 v[4]; float ss = 0.f;
; #pragma unroll
;         for (int j = 0; j < 4; ++j) v[j] = *(const f32x4*)(xr + 4 * F.lane + 256 * j);
;         if (l == 0 && which == 1 && row >= NLAT) {
;             const float* cin = P.in[2] + (size_t)(row - NLAT) * 1024 + 4 * F.lane;
;             const float* pp = (const float*)(P.ws + WS_AR + AR_PG4) + (size_t)(row - NLAT) * 1024 + 4 * F.lane;
;             float* xo = (float*)(P.ws + WS_XC) + (size_t)(row - NLAT) * 1024 + 4 * F.lane;
; #pragma unroll
;             for (int j = 0; j < 4; ++j) {
;                 v[j] = *(const f32x4*)(cin + 256 * j);
; #pragma unroll
;                 for (int kp = 0; kp < 3; ++kp) v[j] += *(const f32x4*)(pp + (size_t)kp * NCTX * 1024 + 256 * j);
;                 *(f32x4*)(xo + 256 * j) = v[j];
;             }
;         }
;         if (l == 1 && which == 0 && row >= NLAT) {
;             const float* pp = (const float*)(P.ws + WS_AR + AR_PART) + (size_t)(row - NLAT) * 1024 + 4 * F.lane;
; #pragma unroll
;             for (int kp = 0; kp < 4; ++kp)
; #pragma unroll
;                 for (int j = 0; j < 4; ++j) v[j] += *(const f32x4*)(pp + (size_t)kp * NCTX * 1024 + 256 * j);
;         }
; #pragma unroll
;         for (int j = 0; j < 4; ++j) ss += (v[j][0] * v[j][0] + v[j][1] * v[j][1]) + (v[j][2] * v[j][2] + v[j][3] * v[j][3]);
;         ss = wave_sum(ss); const float rinv = rsqrtf(ss * (1.0f / 1024.0f) + EPS);
; #pragma unroll
;         for (int j = 0; j < 4; ++j) {
;             const int col = 4 * F.lane + 256 * j;
;             const f32x4 g = *(const f32x4*)(gn + col), s1 = *(const f32x4*)(sc + col), s0 = *(const f32x4*)(sh + col);
;             const f32x4 y = v[j] * rinv * g * (s1 + 1.0f) + s0;
;             u32x2 w; w.x = cvt_pk_bf16(y[0], y[1]); w.y = cvt_pk_bf16(y[2], y[3]);
;             *(u32x2*)(H + (size_t)row * 1024 + col) = w;
.LBB0_570:
	s_min_i32 s2, s6, 0x8000
	s_ashr_i32 s2, s2, 13
	s_mulk_i32 s2, 0x1800
	s_ashr_i32 s3, s2, 31
	s_lshl_b64 s[2:3], s[2:3], 2
	v_readlane_b32 s8, v253, 62
	s_add_u32 s8, s8, s2
	v_readlane_b32 s2, v254, 0
	s_addc_u32 s9, s2, s3
	s_add_u32 s10, s8, 0x1000
	global_load_dwordx4 v[28:31], v[18:19], off
	s_addc_u32 s11, s9, 0
	global_load_dwordx4 v[32:35], v26, s[10:11]
	global_load_dwordx4 v[36:39], v26, s[8:9]
	global_load_dwordx4 v[100:103], v[18:19], off offset:1024
	global_load_dwordx4 v[104:107], v17, s[10:11]
	global_load_dwordx4 v[108:111], v26, s[8:9] offset:1024
	global_load_dwordx4 v[112:115], v[18:19], off offset:2048
	global_load_dwordx4 v[116:119], v24, s[10:11]
	global_load_dwordx4 v[120:123], v26, s[8:9] offset:2048
	global_load_dwordx4 v[124:127], v[18:19], off offset:3072
	global_load_dwordx4 v[128:131], v25, s[10:11]
	global_load_dwordx4 v[132:135], v26, s[8:9] offset:3072
	s_waitcnt vmcnt(0)
	v_mul_f32_e32 v27, v13, v13
	v_mul_f32_e32 v40, v15, v15
	v_mul_f32_e32 v41, v9, v9
	v_mul_f32_e32 v42, v11, v11
	v_mul_f32_e32 v43, v5, v5
	v_mul_f32_e32 v44, v7, v7
	v_fmac_f32_e32 v27, v12, v12
	v_fmac_f32_e32 v40, v14, v14
	v_fmac_f32_e32 v41, v8, v8
	v_fmac_f32_e32 v42, v10, v10
	v_mul_f32_e32 v45, v1, v1
	v_mul_f32_e32 v46, v3, v3
	v_fmac_f32_e32 v43, v4, v4
	v_fmac_f32_e32 v44, v6, v6
	v_add_f32_e32 v27, v27, v40
	v_add_f32_e32 v40, v41, v42
	v_fmac_f32_e32 v45, v0, v0
	v_fmac_f32_e32 v46, v2, v2
	v_add_f32_e32 v41, v43, v44
	v_add_f32_e32 v27, v27, v40
	v_add_f32_e32 v42, v45, v46
	v_add_f32_e32 v27, v41, v27
	v_add_f32_e32 v27, v42, v27
	ds_swizzle_b32 v40, v27 offset:swizzle(SWAP,1)
	s_add_u32 s6, s6, s24
	s_addc_u32 s7, s7, s25
	s_cmp_lt_i32 s6, 0x8400
	s_waitcnt lgkmcnt(0)
	v_add_f32_e32 v27, v27, v40
	ds_swizzle_b32 v40, v27 offset:swizzle(SWAP,2)
	s_waitcnt lgkmcnt(0)
	v_add_f32_e32 v27, v27, v40
	ds_swizzle_b32 v40, v27 offset:swizzle(SWAP,4)
	s_waitcnt lgkmcnt(0)
	v_add_f32_e32 v27, v27, v40
	ds_swizzle_b32 v40, v27 offset:swizzle(SWAP,8)
	s_waitcnt lgkmcnt(0)
	v_add_f32_e32 v27, v27, v40
	ds_swizzle_b32 v40, v27 offset:swizzle(SWAP,16)
	s_waitcnt lgkmcnt(0)
	v_add_f32_e32 v27, v27, v40
	v_mov_b32_e32 v40, v27
	s_nop 1
	v_permlane32_swap_b32_e32 v27, v40
	v_add_f32_e32 v27, v27, v40
	v_fmamk_f32 v27, v27, 0x3a800000, v226
	v_mul_f32_e32 v40, 0x4b800000, v27
	v_cmp_gt_f32_e32 vcc, s12, v27
	s_nop 1
	v_cndmask_b32_e32 v27, v27, v40, vcc
	v_rsq_f32_e32 v27, v27
	s_nop 0
	v_mul_f32_e32 v40, 0x45800000, v27
	v_cndmask_b32_e32 v40, v27, v40, vcc
	v_pk_mul_f32 v[14:15], v[14:15], v[40:41] op_sel_hi:[1,0]
	v_pk_mul_f32 v[12:13], v[12:13], v[40:41] op_sel_hi:[1,0]
	v_pk_mul_f32 v[10:11], v[10:11], v[40:41] op_sel_hi:[1,0]
	v_pk_mul_f32 v[8:9], v[8:9], v[40:41] op_sel_hi:[1,0]
	v_pk_mul_f32 v[6:7], v[6:7], v[40:41] op_sel_hi:[1,0]
	v_pk_mul_f32 v[4:5], v[4:5], v[40:41] op_sel_hi:[1,0]
	v_pk_mul_f32 v[2:3], v[2:3], v[40:41] op_sel_hi:[1,0]
	v_pk_mul_f32 v[0:1], v[0:1], v[40:41] op_sel_hi:[1,0]
	v_pk_mul_f32 v[12:13], v[28:29], v[12:13]
	v_pk_mul_f32 v[14:15], v[30:31], v[14:15]
	v_pk_add_f32 v[28:29], v[34:35], 1.0 op_sel_hi:[1,0]
	v_pk_add_f32 v[30:31], v[32:33], 1.0 op_sel_hi:[1,0]
	v_pk_fma_f32 v[14:15], v[28:29], v[14:15], v[38:39]
	v_pk_fma_f32 v[12:13], v[30:31], v[12:13], v[36:37]
	s_nop 0
	v_cvt_pk_bf16_f32 v12, v12, v13
	v_cvt_pk_bf16_f32 v13, v14, v15
	global_store_dwordx2 v[22:23], v[12:13], off
	s_nop 0
	v_mov_b32_e32 v12, v100
	v_mov_b32_e32 v13, v101
	v_mov_b32_e32 v14, v102
	v_mov_b32_e32 v15, v103
	v_pk_mul_f32 v[8:9], v[12:13], v[8:9]
	v_pk_mul_f32 v[10:11], v[14:15], v[10:11]
	v_mov_b32_e32 v28, v104
	v_mov_b32_e32 v29, v105
	v_mov_b32_e32 v30, v106
	v_mov_b32_e32 v31, v107
	v_pk_add_f32 v[12:13], v[30:31], 1.0 op_sel_hi:[1,0]
	v_pk_add_f32 v[14:15], v[28:29], 1.0 op_sel_hi:[1,0]
	v_mov_b32_e32 v32, v108
	v_mov_b32_e32 v33, v109
	v_mov_b32_e32 v34, v110
	v_mov_b32_e32 v35, v111
	v_pk_fma_f32 v[10:11], v[12:13], v[10:11], v[34:35]
	v_pk_fma_f32 v[8:9], v[14:15], v[8:9], v[32:33]
	s_nop 0
	v_cvt_pk_bf16_f32 v8, v8, v9
	v_cvt_pk_bf16_f32 v9, v10, v11
	global_store_dwordx2 v[22:23], v[8:9], off offset:512
	s_nop 0
	v_mov_b32_e32 v8, v112
	v_mov_b32_e32 v9, v113
	v_mov_b32_e32 v10, v114
	v_mov_b32_e32 v11, v115
	v_pk_mul_f32 v[4:5], v[8:9], v[4:5]
	v_pk_mul_f32 v[6:7], v[10:11], v[6:7]
	v_mov_b32_e32 v12, v116
	v_mov_b32_e32 v13, v117
	v_mov_b32_e32 v14, v118
	v_mov_b32_e32 v15, v119
	v_pk_add_f32 v[8:9], v[14:15], 1.0 op_sel_hi:[1,0]
	v_pk_add_f32 v[10:11], v[12:13], 1.0 op_sel_hi:[1,0]
	v_mov_b32_e32 v28, v120
	v_mov_b32_e32 v29, v121
	v_mov_b32_e32 v30, v122
	v_mov_b32_e32 v31, v123
	v_pk_fma_f32 v[6:7], v[8:9], v[6:7], v[30:31]
	v_pk_fma_f32 v[4:5], v[10:11], v[4:5], v[28:29]
	s_nop 0
	v_cvt_pk_bf16_f32 v4, v4, v5
	v_cvt_pk_bf16_f32 v5, v6, v7
	global_store_dwordx2 v[22:23], v[4:5], off offset:1024
	s_nop 0
	v_mov_b32_e32 v4, v124
	v_mov_b32_e32 v5, v125
	v_mov_b32_e32 v6, v126
	v_mov_b32_e32 v7, v127
	v_pk_mul_f32 v[0:1], v[0:1], v[4:5]
	v_pk_mul_f32 v[2:3], v[2:3], v[6:7]
	v_mov_b32_e32 v8, v128
	v_mov_b32_e32 v9, v129
	v_mov_b32_e32 v10, v130
	v_mov_b32_e32 v11, v131
	v_pk_add_f32 v[4:5], v[10:11], 1.0 op_sel_hi:[1,0]
	v_pk_add_f32 v[6:7], v[8:9], 1.0 op_sel_hi:[1,0]
	v_mov_b32_e32 v12, v132
	v_mov_b32_e32 v13, v133
	v_mov_b32_e32 v14, v134
	v_mov_b32_e32 v15, v135
	v_pk_fma_f32 v[2:3], v[2:3], v[4:5], v[14:15]
	v_pk_fma_f32 v[0:1], v[0:1], v[6:7], v[12:13]
	s_nop 0
	v_cvt_pk_bf16_f32 v0, v0, v1
	v_cvt_pk_bf16_f32 v1, v2, v3
	global_store_dwordx2 v[22:23], v[0:1], off offset:1536
	v_lshl_add_u64 v[22:23], v[22:23], 0, s[0:1]
	s_cbranch_scc0 .LBB0_573
